# s19 + p5_plain_safe: P5 activations stored write-back as well (same-XCD consumer in P6; write-back fallback at barrier 5 when placement is not verified)
# speedup vs baseline: 1.0094x; 1.0037x over previous
.LBB0_608:
	v_lshl_or_b32 v145, s56, 23, v172
	ds_read_b32 v144, v164
	ds_read_b32 v146, v165
	ds_read_b32 v148, v166
	ds_read_b32 v150, v167
	ds_read_b32 v152, v168
	ds_read_b32 v154, v169
	ds_read_b32 v156, v170
	ds_read_b32 v158, v171
	s_waitcnt lgkmcnt(0)
	v_pk_mul_f32 v[120:121], v[120:121], v[144:145] op_sel_hi:[1,0]
	v_pk_mul_f32 v[126:127], v[126:127], v[144:145] op_sel_hi:[1,0]
	v_pk_mul_f32 v[124:125], v[124:125], v[144:145] op_sel_hi:[1,0]
	v_pk_mul_f32 v[122:123], v[122:123], v[144:145] op_sel_hi:[1,0]
	v_max_f32_e32 v120, 0, v120
	v_max_f32_e32 v121, 0, v121
	v_max_f32_e32 v124, 0, v124
	v_max_f32_e32 v125, 0, v125
	v_pk_mul_f32 v[178:179], v[120:121], v[120:121]
	v_max_f32_e32 v120, 0, v126
	v_max_f32_e32 v122, 0, v122
	v_max_f32_e32 v121, 0, v127
	v_max_f32_e32 v123, 0, v123
	s_lshl_b32 s16, s34, 15
	v_pk_mul_f32 v[124:125], v[124:125], v[124:125]
	v_pk_mul_f32 v[126:127], v[120:121], v[120:121]
	v_pk_mul_f32 v[180:181], v[122:123], v[122:123]
	v_pk_mul_f32 v[104:105], v[104:105], v[144:145] op_sel_hi:[1,0]
	v_add3_u32 v147, s16, v149, v145
	v_cvt_pk_bf16_f32 v120, v124, v125
	v_cvt_pk_bf16_f32 v121, v126, v127
	v_cvt_pk_bf16_f32 v122, v178, v179
	v_cvt_pk_bf16_f32 v123, v180, v181
	v_pk_mul_f32 v[114:115], v[114:115], v[144:145] op_sel_hi:[1,0]
	v_pk_mul_f32 v[112:113], v[112:113], v[144:145] op_sel_hi:[1,0]
	v_pk_mul_f32 v[106:107], v[106:107], v[144:145] op_sel_hi:[1,0]
	v_max_f32_e32 v104, 0, v104
	v_max_f32_e32 v105, 0, v105
	buffer_store_dwordx4 v[120:123], v147, s[8:11], 0 offen
	v_max_f32_e32 v112, 0, v112
	v_max_f32_e32 v113, 0, v113
	v_pk_mul_f32 v[120:121], v[104:105], v[104:105]
	v_max_f32_e32 v104, 0, v114
	v_max_f32_e32 v106, 0, v106
	v_max_f32_e32 v105, 0, v115
	v_max_f32_e32 v107, 0, v107
	v_pk_mul_f32 v[112:113], v[112:113], v[112:113]
	v_pk_mul_f32 v[114:115], v[104:105], v[104:105]
	v_pk_mul_f32 v[122:123], v[106:107], v[106:107]
	v_cvt_pk_bf16_f32 v104, v112, v113
	v_cvt_pk_bf16_f32 v105, v114, v115
	v_cvt_pk_bf16_f32 v106, v120, v121
	v_cvt_pk_bf16_f32 v107, v122, v123
	v_add_u32_e32 v112, 0x400000, v147
	buffer_store_dwordx4 v[104:107], v112, s[8:11], 0 offen
	v_pk_mul_f32 v[110:111], v[110:111], v[146:147] op_sel_hi:[1,0]
	v_pk_mul_f32 v[108:109], v[108:109], v[146:147] op_sel_hi:[1,0]
	v_pk_mul_f32 v[104:105], v[118:119], v[146:147] op_sel_hi:[1,0]
	v_pk_mul_f32 v[106:107], v[116:117], v[146:147] op_sel_hi:[1,0]
	v_max_f32_e32 v108, 0, v108
	v_max_f32_e32 v106, 0, v106
	v_max_f32_e32 v107, 0, v107
	v_max_f32_e32 v109, 0, v109
	v_max_f32_e32 v104, 0, v104
	v_max_f32_e32 v110, 0, v110
	v_max_f32_e32 v105, 0, v105
	v_max_f32_e32 v111, 0, v111
	v_pk_mul_f32 v[106:107], v[106:107], v[106:107]
	v_pk_mul_f32 v[108:109], v[108:109], v[108:109]
	v_pk_mul_f32 v[112:113], v[104:105], v[104:105]
	v_pk_mul_f32 v[110:111], v[110:111], v[110:111]
	v_pk_mul_f32 v[88:89], v[88:89], v[146:147] op_sel_hi:[1,0]
	v_add3_u32 v114, s16, v155, v145
	v_cvt_pk_bf16_f32 v104, v106, v107
	v_cvt_pk_bf16_f32 v105, v112, v113
	v_cvt_pk_bf16_f32 v106, v108, v109
	v_cvt_pk_bf16_f32 v107, v110, v111
	v_pk_mul_f32 v[98:99], v[98:99], v[146:147] op_sel_hi:[1,0]
	v_pk_mul_f32 v[96:97], v[96:97], v[146:147] op_sel_hi:[1,0]
	v_pk_mul_f32 v[90:91], v[90:91], v[146:147] op_sel_hi:[1,0]
	v_max_f32_e32 v88, 0, v88
	v_max_f32_e32 v89, 0, v89
	buffer_store_dwordx4 v[104:107], v114, s[8:11], 0 offen
	v_max_f32_e32 v96, 0, v96
	v_max_f32_e32 v97, 0, v97
	v_pk_mul_f32 v[104:105], v[88:89], v[88:89]
	v_max_f32_e32 v88, 0, v98
	v_max_f32_e32 v90, 0, v90
	v_max_f32_e32 v89, 0, v99
	v_max_f32_e32 v91, 0, v91
	v_pk_mul_f32 v[96:97], v[96:97], v[96:97]
	v_pk_mul_f32 v[98:99], v[88:89], v[88:89]
	v_pk_mul_f32 v[106:107], v[90:91], v[90:91]
	v_cvt_pk_bf16_f32 v88, v96, v97
	v_cvt_pk_bf16_f32 v89, v98, v99
	v_cvt_pk_bf16_f32 v90, v104, v105
	v_cvt_pk_bf16_f32 v91, v106, v107
	v_add_u32_e32 v96, 0x400000, v114
	buffer_store_dwordx4 v[88:91], v96, s[8:11], 0 offen
	v_pk_mul_f32 v[94:95], v[94:95], v[148:149] op_sel_hi:[1,0]
	v_pk_mul_f32 v[92:93], v[92:93], v[148:149] op_sel_hi:[1,0]
	v_pk_mul_f32 v[88:89], v[102:103], v[148:149] op_sel_hi:[1,0]
	v_pk_mul_f32 v[90:91], v[100:101], v[148:149] op_sel_hi:[1,0]
	v_max_f32_e32 v92, 0, v92
	v_max_f32_e32 v90, 0, v90
	v_max_f32_e32 v91, 0, v91
	v_max_f32_e32 v93, 0, v93
	v_max_f32_e32 v88, 0, v88
	v_max_f32_e32 v94, 0, v94
	v_max_f32_e32 v89, 0, v89
	v_max_f32_e32 v95, 0, v95
	v_pk_mul_f32 v[90:91], v[90:91], v[90:91]
	v_pk_mul_f32 v[92:93], v[92:93], v[92:93]
	v_pk_mul_f32 v[96:97], v[88:89], v[88:89]
	v_pk_mul_f32 v[94:95], v[94:95], v[94:95]
	v_pk_mul_f32 v[72:73], v[72:73], v[148:149] op_sel_hi:[1,0]
	v_add3_u32 v98, s16, v157, v145
	v_cvt_pk_bf16_f32 v88, v90, v91
	v_cvt_pk_bf16_f32 v89, v96, v97
	v_cvt_pk_bf16_f32 v90, v92, v93
	v_cvt_pk_bf16_f32 v91, v94, v95
	v_pk_mul_f32 v[82:83], v[82:83], v[148:149] op_sel_hi:[1,0]
	v_pk_mul_f32 v[80:81], v[80:81], v[148:149] op_sel_hi:[1,0]
	v_pk_mul_f32 v[74:75], v[74:75], v[148:149] op_sel_hi:[1,0]
	v_max_f32_e32 v72, 0, v72
	v_max_f32_e32 v73, 0, v73
	buffer_store_dwordx4 v[88:91], v98, s[8:11], 0 offen
	v_max_f32_e32 v80, 0, v80
	v_max_f32_e32 v81, 0, v81
	v_pk_mul_f32 v[88:89], v[72:73], v[72:73]
	v_max_f32_e32 v72, 0, v82
	v_max_f32_e32 v74, 0, v74
	v_max_f32_e32 v73, 0, v83
	v_max_f32_e32 v75, 0, v75
	v_pk_mul_f32 v[80:81], v[80:81], v[80:81]
	v_pk_mul_f32 v[82:83], v[72:73], v[72:73]
	v_pk_mul_f32 v[90:91], v[74:75], v[74:75]
	v_cvt_pk_bf16_f32 v72, v80, v81
	v_cvt_pk_bf16_f32 v73, v82, v83
	v_cvt_pk_bf16_f32 v74, v88, v89
	v_cvt_pk_bf16_f32 v75, v90, v91
	v_add_u32_e32 v80, 0x400000, v98
	buffer_store_dwordx4 v[72:75], v80, s[8:11], 0 offen
	v_pk_mul_f32 v[78:79], v[78:79], v[150:151] op_sel_hi:[1,0]
	v_pk_mul_f32 v[76:77], v[76:77], v[150:151] op_sel_hi:[1,0]
	v_pk_mul_f32 v[72:73], v[86:87], v[150:151] op_sel_hi:[1,0]
	v_pk_mul_f32 v[74:75], v[84:85], v[150:151] op_sel_hi:[1,0]
	v_max_f32_e32 v76, 0, v76
	v_max_f32_e32 v74, 0, v74
	v_max_f32_e32 v75, 0, v75
	v_max_f32_e32 v77, 0, v77
	v_max_f32_e32 v72, 0, v72
	v_max_f32_e32 v78, 0, v78
	v_max_f32_e32 v73, 0, v73
	v_max_f32_e32 v79, 0, v79
	v_pk_mul_f32 v[74:75], v[74:75], v[74:75]
	v_pk_mul_f32 v[76:77], v[76:77], v[76:77]
	v_pk_mul_f32 v[80:81], v[72:73], v[72:73]
	v_pk_mul_f32 v[78:79], v[78:79], v[78:79]
	v_pk_mul_f32 v[64:65], v[64:65], v[150:151] op_sel_hi:[1,0]
	v_add3_u32 v82, s16, v159, v145
	v_cvt_pk_bf16_f32 v72, v74, v75
	v_cvt_pk_bf16_f32 v73, v80, v81
	v_cvt_pk_bf16_f32 v74, v76, v77
	v_cvt_pk_bf16_f32 v75, v78, v79
	v_pk_mul_f32 v[70:71], v[70:71], v[150:151] op_sel_hi:[1,0]
	v_pk_mul_f32 v[68:69], v[68:69], v[150:151] op_sel_hi:[1,0]
	v_pk_mul_f32 v[66:67], v[66:67], v[150:151] op_sel_hi:[1,0]
	v_max_f32_e32 v64, 0, v64
	v_max_f32_e32 v65, 0, v65
	buffer_store_dwordx4 v[72:75], v82, s[8:11], 0 offen
	v_max_f32_e32 v68, 0, v68
	v_max_f32_e32 v69, 0, v69
	v_pk_mul_f32 v[72:73], v[64:65], v[64:65]
	v_max_f32_e32 v64, 0, v70
	v_max_f32_e32 v66, 0, v66
	v_max_f32_e32 v65, 0, v71
	v_max_f32_e32 v67, 0, v67
	v_pk_mul_f32 v[68:69], v[68:69], v[68:69]
	v_pk_mul_f32 v[70:71], v[64:65], v[64:65]
	v_pk_mul_f32 v[74:75], v[66:67], v[66:67]
	v_pk_mul_f32 v[56:57], v[56:57], v[152:153] op_sel_hi:[1,0]
	v_cvt_pk_bf16_f32 v64, v68, v69
	v_cvt_pk_bf16_f32 v65, v70, v71
	v_cvt_pk_bf16_f32 v66, v72, v73
	v_cvt_pk_bf16_f32 v67, v74, v75
	v_add_u32_e32 v68, 0x400000, v82
	v_pk_mul_f32 v[62:63], v[62:63], v[152:153] op_sel_hi:[1,0]
	v_pk_mul_f32 v[60:61], v[60:61], v[152:153] op_sel_hi:[1,0]
	v_pk_mul_f32 v[58:59], v[58:59], v[152:153] op_sel_hi:[1,0]
	v_max_f32_e32 v56, 0, v56
	v_max_f32_e32 v57, 0, v57
	buffer_store_dwordx4 v[64:67], v68, s[8:11], 0 offen
	v_max_f32_e32 v60, 0, v60
	v_max_f32_e32 v61, 0, v61
	v_pk_mul_f32 v[64:65], v[56:57], v[56:57]
	v_max_f32_e32 v56, 0, v62
	v_max_f32_e32 v58, 0, v58
	v_max_f32_e32 v57, 0, v63
	v_max_f32_e32 v59, 0, v59
	v_pk_mul_f32 v[60:61], v[60:61], v[60:61]
	v_pk_mul_f32 v[62:63], v[56:57], v[56:57]
	v_pk_mul_f32 v[66:67], v[58:59], v[58:59]
	v_pk_mul_f32 v[40:41], v[40:41], v[152:153] op_sel_hi:[1,0]
	v_add3_u32 v68, s16, v160, v145
	v_cvt_pk_bf16_f32 v56, v60, v61
	v_cvt_pk_bf16_f32 v57, v62, v63
	v_cvt_pk_bf16_f32 v58, v64, v65
	v_cvt_pk_bf16_f32 v59, v66, v67
	v_pk_mul_f32 v[50:51], v[50:51], v[152:153] op_sel_hi:[1,0]
	v_pk_mul_f32 v[48:49], v[48:49], v[152:153] op_sel_hi:[1,0]
	v_pk_mul_f32 v[42:43], v[42:43], v[152:153] op_sel_hi:[1,0]
	v_max_f32_e32 v40, 0, v40
	v_max_f32_e32 v41, 0, v41
	buffer_store_dwordx4 v[56:59], v68, s[8:11], 0 offen
	v_max_f32_e32 v48, 0, v48
	v_max_f32_e32 v49, 0, v49
	v_pk_mul_f32 v[56:57], v[40:41], v[40:41]
	v_max_f32_e32 v40, 0, v50
	v_max_f32_e32 v42, 0, v42
	v_max_f32_e32 v41, 0, v51
	v_max_f32_e32 v43, 0, v43
	v_pk_mul_f32 v[48:49], v[48:49], v[48:49]
	v_pk_mul_f32 v[50:51], v[40:41], v[40:41]
	v_pk_mul_f32 v[58:59], v[42:43], v[42:43]
	v_cvt_pk_bf16_f32 v40, v48, v49
	v_cvt_pk_bf16_f32 v41, v50, v51
	v_cvt_pk_bf16_f32 v42, v56, v57
	v_cvt_pk_bf16_f32 v43, v58, v59
	v_add_u32_e32 v48, 0x400000, v68
	buffer_store_dwordx4 v[40:43], v48, s[8:11], 0 offen
	v_pk_mul_f32 v[46:47], v[46:47], v[154:155] op_sel_hi:[1,0]
	v_pk_mul_f32 v[44:45], v[44:45], v[154:155] op_sel_hi:[1,0]
	v_pk_mul_f32 v[40:41], v[54:55], v[154:155] op_sel_hi:[1,0]
	v_pk_mul_f32 v[42:43], v[52:53], v[154:155] op_sel_hi:[1,0]
	v_max_f32_e32 v44, 0, v44
	v_max_f32_e32 v42, 0, v42
	v_max_f32_e32 v43, 0, v43
	v_max_f32_e32 v45, 0, v45
	v_max_f32_e32 v40, 0, v40
	v_max_f32_e32 v46, 0, v46
	v_max_f32_e32 v41, 0, v41
	v_max_f32_e32 v47, 0, v47
	v_pk_mul_f32 v[42:43], v[42:43], v[42:43]
	v_pk_mul_f32 v[44:45], v[44:45], v[44:45]
	v_pk_mul_f32 v[48:49], v[40:41], v[40:41]
	v_pk_mul_f32 v[46:47], v[46:47], v[46:47]
	v_pk_mul_f32 v[24:25], v[24:25], v[154:155] op_sel_hi:[1,0]
	v_add3_u32 v50, s16, v161, v145
	v_cvt_pk_bf16_f32 v40, v42, v43
	v_cvt_pk_bf16_f32 v41, v48, v49
	v_cvt_pk_bf16_f32 v42, v44, v45
	v_cvt_pk_bf16_f32 v43, v46, v47
	v_pk_mul_f32 v[34:35], v[34:35], v[154:155] op_sel_hi:[1,0]
	v_pk_mul_f32 v[32:33], v[32:33], v[154:155] op_sel_hi:[1,0]
	v_pk_mul_f32 v[26:27], v[26:27], v[154:155] op_sel_hi:[1,0]
	v_max_f32_e32 v24, 0, v24
	v_max_f32_e32 v25, 0, v25
	buffer_store_dwordx4 v[40:43], v50, s[8:11], 0 offen
	v_max_f32_e32 v32, 0, v32
	v_max_f32_e32 v33, 0, v33
	v_pk_mul_f32 v[40:41], v[24:25], v[24:25]
	v_max_f32_e32 v24, 0, v34
	v_max_f32_e32 v26, 0, v26
	v_max_f32_e32 v25, 0, v35
	v_max_f32_e32 v27, 0, v27
	v_pk_mul_f32 v[32:33], v[32:33], v[32:33]
	v_pk_mul_f32 v[34:35], v[24:25], v[24:25]
	v_pk_mul_f32 v[42:43], v[26:27], v[26:27]
	v_cvt_pk_bf16_f32 v24, v32, v33
	v_cvt_pk_bf16_f32 v25, v34, v35
	v_cvt_pk_bf16_f32 v26, v40, v41
	v_cvt_pk_bf16_f32 v27, v42, v43
	v_add_u32_e32 v32, 0x400000, v50
	buffer_store_dwordx4 v[24:27], v32, s[8:11], 0 offen
	v_pk_mul_f32 v[30:31], v[30:31], v[156:157] op_sel_hi:[1,0]
	v_pk_mul_f32 v[28:29], v[28:29], v[156:157] op_sel_hi:[1,0]
	v_pk_mul_f32 v[24:25], v[38:39], v[156:157] op_sel_hi:[1,0]
	v_pk_mul_f32 v[26:27], v[36:37], v[156:157] op_sel_hi:[1,0]
	v_max_f32_e32 v28, 0, v28
	v_max_f32_e32 v26, 0, v26
	v_max_f32_e32 v27, 0, v27
	v_max_f32_e32 v29, 0, v29
	v_max_f32_e32 v24, 0, v24
	v_max_f32_e32 v30, 0, v30
	v_max_f32_e32 v25, 0, v25
	v_max_f32_e32 v31, 0, v31
	v_pk_mul_f32 v[26:27], v[26:27], v[26:27]
	v_pk_mul_f32 v[28:29], v[28:29], v[28:29]
	v_pk_mul_f32 v[32:33], v[24:25], v[24:25]
	v_pk_mul_f32 v[30:31], v[30:31], v[30:31]
	v_pk_mul_f32 v[12:13], v[12:13], v[156:157] op_sel_hi:[1,0]
	v_add3_u32 v34, s16, v162, v145
	v_cvt_pk_bf16_f32 v24, v26, v27
	v_cvt_pk_bf16_f32 v25, v32, v33
	v_cvt_pk_bf16_f32 v26, v28, v29
	v_cvt_pk_bf16_f32 v27, v30, v31
	v_pk_mul_f32 v[22:23], v[22:23], v[156:157] op_sel_hi:[1,0]
	v_pk_mul_f32 v[20:21], v[20:21], v[156:157] op_sel_hi:[1,0]
	v_pk_mul_f32 v[14:15], v[14:15], v[156:157] op_sel_hi:[1,0]
	v_max_f32_e32 v12, 0, v12
	v_max_f32_e32 v13, 0, v13
	buffer_store_dwordx4 v[24:27], v34, s[8:11], 0 offen
	v_max_f32_e32 v20, 0, v20
	v_max_f32_e32 v21, 0, v21
	v_pk_mul_f32 v[24:25], v[12:13], v[12:13]
	v_max_f32_e32 v12, 0, v22
	v_max_f32_e32 v14, 0, v14
	v_max_f32_e32 v13, 0, v23
	v_max_f32_e32 v15, 0, v15
	v_pk_mul_f32 v[20:21], v[20:21], v[20:21]
	v_pk_mul_f32 v[22:23], v[12:13], v[12:13]
	v_pk_mul_f32 v[26:27], v[14:15], v[14:15]
	v_cvt_pk_bf16_f32 v12, v20, v21
	v_cvt_pk_bf16_f32 v13, v22, v23
	v_cvt_pk_bf16_f32 v14, v24, v25
	v_cvt_pk_bf16_f32 v15, v26, v27
	v_add_u32_e32 v20, 0x400000, v34
	v_pk_mul_f32 v[8:9], v[8:9], v[158:159] op_sel_hi:[1,0]
	buffer_store_dwordx4 v[12:15], v20, s[8:11], 0 offen
	v_pk_mul_f32 v[10:11], v[10:11], v[158:159] op_sel_hi:[1,0]
	v_max_f32_e32 v8, 0, v8
	v_pk_mul_f32 v[12:13], v[18:19], v[158:159] op_sel_hi:[1,0]
	v_pk_mul_f32 v[14:15], v[16:17], v[158:159] op_sel_hi:[1,0]
	v_max_f32_e32 v9, 0, v9
	v_max_f32_e32 v14, 0, v14
	v_max_f32_e32 v15, 0, v15
	v_pk_mul_f32 v[16:17], v[8:9], v[8:9]
	v_max_f32_e32 v8, 0, v12
	v_max_f32_e32 v10, 0, v10
	v_max_f32_e32 v9, 0, v13
	v_max_f32_e32 v11, 0, v11
	v_pk_mul_f32 v[14:15], v[14:15], v[14:15]
	v_pk_mul_f32 v[12:13], v[8:9], v[8:9]
	v_pk_mul_f32 v[18:19], v[10:11], v[10:11]
	v_pk_mul_f32 v[0:1], v[0:1], v[158:159] op_sel_hi:[1,0]
	v_add3_u32 v20, s16, v163, v145
	v_cvt_pk_bf16_f32 v8, v14, v15
	v_cvt_pk_bf16_f32 v9, v12, v13
	v_cvt_pk_bf16_f32 v10, v16, v17
	v_cvt_pk_bf16_f32 v11, v18, v19
	v_pk_mul_f32 v[6:7], v[6:7], v[158:159] op_sel_hi:[1,0]
	v_pk_mul_f32 v[4:5], v[4:5], v[158:159] op_sel_hi:[1,0]
	v_pk_mul_f32 v[2:3], v[2:3], v[158:159] op_sel_hi:[1,0]
	v_max_f32_e32 v0, 0, v0
	v_max_f32_e32 v1, 0, v1
	buffer_store_dwordx4 v[8:11], v20, s[8:11], 0 offen
	v_max_f32_e32 v4, 0, v4
	v_max_f32_e32 v5, 0, v5
	v_pk_mul_f32 v[8:9], v[0:1], v[0:1]
	v_max_f32_e32 v0, 0, v6
	v_max_f32_e32 v2, 0, v2
	v_max_f32_e32 v1, 0, v7
	v_max_f32_e32 v3, 0, v3
	v_pk_mul_f32 v[4:5], v[4:5], v[4:5]
	v_pk_mul_f32 v[6:7], v[0:1], v[0:1]
	v_pk_mul_f32 v[10:11], v[2:3], v[2:3]
	v_cvt_pk_bf16_f32 v0, v4, v5
	v_cvt_pk_bf16_f32 v1, v6, v7
	v_cvt_pk_bf16_f32 v2, v8, v9
	v_cvt_pk_bf16_f32 v3, v10, v11
	v_add_u32_e32 v4, 0x400000, v20
	s_andn2_b64 vcc, exec, s[4:5]
	s_mov_b64 s[4:5], -1
	buffer_store_dwordx4 v[0:3], v4, s[8:11], 0 offen
	s_cbranch_vccnz .LBB0_591
	s_andn2_b64 vcc, exec, s[18:19]
	s_cbranch_vccnz .LBB0_590
	s_barrier
	s_branch .LBB0_590

.LBB0_612:
	s_cmp_gt_i32 s83, 6
	s_cselect_b64 s[0:1], -1, 0
	s_and_b64 s[4:5], s[6:7], s[0:1]
	s_andn2_b64 vcc, exec, s[4:5]
	s_cbranch_vccnz .LBB0_666
	s_waitcnt vmcnt(0)
	s_waitcnt vmcnt(0) lgkmcnt(0)
	s_barrier
	s_and_saveexec_b64 s[4:5], s[94:95]
	s_cbranch_execz .LBB0_665
	v_readlane_b32 s9, v255, 63
	s_nop 0
	s_cmp_eq_u32 s9, 0
	s_cbranch_scc1 .Lxb_loc_5
	buffer_wbl2 sc1
	s_waitcnt vmcnt(0)
.Lxb_loc_5:
	v_mov_b32_e32 v1, 0x23ff0
	ds_read_b32 v2, v1
	ds_read_b32 v3, v1 offset:4
	s_add_u32 s6, s80, 0x2380000
	s_addc_u32 s7, s81, 0
	s_lshl_b32 s8, s87, 8
	s_add_i32 s9, s8, 0x1400
	s_add_i32 s8, s8, 0x2400
	v_mov_b32_e32 v4, s9
	v_mov_b32_e32 v5, 1
	global_atomic_add v6, v4, v5, s[6:7] sc0
	buffer_inv sc1
	s_waitcnt vmcnt(0) lgkmcnt(0)
	v_readfirstlane_b32 s10, v6
	v_readfirstlane_b32 s11, v2
	v_readfirstlane_b32 s16, v3
	s_add_i32 s10, s10, 1
	s_mul_i32 s11, s11, 6
	s_cmp_lg_u32 s10, s11
	s_cbranch_scc1 .Lxb_nl_5
	v_readlane_b32 s9, v255, 63
	s_nop 0
	s_cmp_lg_u32 s9, 0
	s_cbranch_scc1 .Lxb_glob_5
	v_mov_b32_e32 v4, s8
	global_atomic_add v4, v5, s[6:7]
	s_branch .Lxb_done_5
